# phase A K-loop: two staging register sets (2-deep prefetch, AGPRs as staging) with the tile loads spread between the MFMAs
# speedup vs baseline: 1.0162x; 1.0058x over previous
; template <bool ABF, bool BBF, class RowF, class ColF, class Epi>
; __device__ __forceinline__ void gemm_tile(char* smem, int K, RowF rowptr, ColF colptr, int ldb, Epi epi) {
;     ...
;   f32x4 acc[4][4];
; #pragma unroll
;   for (int i = 0; i < 4; i++)
; #pragma unroll
;     for (int j = 0; j < 4; j++) acc[i][j] = f32x4{0.f, 0.f, 0.f, 0.f};
;   constexpr int NA = ABF ? 4 : 8;
;   const int ar0 = ABF ? (tid >> 3) : (tid >> 4);
;   const int ac = ABF ? (tid & 7) * 8 : (tid & 15) * 4;
;   constexpr int ARS = ABF ? 32 : 16;
;   const char* ap[NA];
; #pragma unroll
;   for (int i = 0; i < NA; i++) ap[i] = (const char*)rowptr(ar0 + ARS * i) + ac * (ABF ? 2 : 4);
;   const int bc = tid & 127, kh = tid >> 7;
;   const float* bp = BBF ? nullptr : ((const float*)colptr(bc) + (size_t)(kh * 32) * ldb);
;   const int br0 = tid >> 3, bcc = (tid & 7) * 8;
;   const char* bq[4];
;   if (BBF) {
; #pragma unroll
;     for (int i = 0; i < 4; i++) bq[i] = (const char*)colptr(br0 + 32 * i) + bcc * 2;
;   }
;   u32x4 ra[NA];
;   float rb[BBF ? 1 : 32];
;   u32x4 rbb[BBF ? 4 : 1];
;   auto gload = [&](int k0) {
; #pragma unroll
;     for (int i = 0; i < NA; i++) ra[i] = *(const u32x4*)(ap[i] + (size_t)k0 * (ABF ? 2 : 4));
;     if (BBF) {
; #pragma unroll
;       for (int i = 0; i < 4; i++) rbb[BBF ? i : 0] = *(const u32x4*)(bq[i] + (size_t)k0 * 2);
;     } else {
;       const float* b = bp + (size_t)k0 * ldb;
; #pragma unroll
;       for (int j = 0; j < 32; j++) rb[BBF ? 0 : j] = b[(size_t)j * ldb];
;     }
;   };
;     ...
;   gload(0);
;   sstore(0);
;   __syncthreads();
.LBB0_108:
	s_andn2_saveexec_b64 s[0:1], s[0:1]
	s_mov_b32 s2, 0x55555556
	v_mul_hi_i32 v1, v0, s2
	v_lshrrev_b32_e32 v2, 31, v1
	v_add_u32_e32 v1, v1, v2
	v_lshl_add_u32 v2, v1, 1, v1
	v_sub_u32_e32 v0, v0, v2
	v_add_u32_e32 v121, s97, v0
	s_or_b64 exec, exec, s[0:1]
	v_lshlrev_b32_e32 v104, 7, v1
	v_ashrrev_i32_e32 v105, 31, v104
	v_lshlrev_b64 v[0:1], 11, v[104:105]
	v_lshl_add_u64 v[2:3], v[98:99], 0, v[0:1]
	v_lshlrev_b32_e32 v137, 7, v121
	v_add_co_u32_e32 v16, vcc, s40, v2
	v_or_b32_e32 v4, v137, v160
	s_nop 0
	v_addc_co_u32_e32 v17, vcc, 0, v3, vcc
	v_min_i32_e32 v10, 0xdef, v4
	v_add_co_u32_e32 v18, vcc, s41, v2
	v_min_i32_e32 v6, 0xe0f, v4
	v_ashrrev_i32_e32 v11, 31, v10
	v_addc_co_u32_e32 v19, vcc, 0, v3, vcc
	v_ashrrev_i32_e32 v7, 31, v6
	v_lshlrev_b64 v[10:11], 11, v[10:11]
	v_min_i32_e32 v12, 0xdcf, v4
	global_load_dwordx4 v[64:67], v[2:3], off
	global_load_dwordx4 v[220:223], v[2:3], off offset:128
	v_add_co_u32_e32 v2, vcc, s42, v2
	v_lshlrev_b64 v[6:7], 11, v[6:7]
	v_lshl_add_u64 v[10:11], v[100:101], 0, v[10:11]
	v_ashrrev_i32_e32 v13, 31, v12
	v_addc_co_u32_e32 v3, vcc, 0, v3, vcc
	v_lshl_add_u64 v[8:9], v[100:101], 0, v[6:7]
	v_lshlrev_b64 v[12:13], 11, v[12:13]
	v_min_i32_e32 v14, 0xdaf, v4
	global_load_dwordx4 v[68:71], v[16:17], off
	global_load_dwordx4 v[224:227], v[16:17], off offset:128
	global_load_dwordx4 v[72:75], v[18:19], off
	global_load_dwordx4 v[228:231], v[18:19], off offset:128
	global_load_dwordx4 v[76:79], v[2:3], off
	global_load_dwordx4 v[232:235], v[2:3], off offset:128
	global_load_dwordx4 v[80:83], v[8:9], off
	global_load_dwordx4 v[236:239], v[8:9], off offset:128
	v_add_co_u32_e32 v2, vcc, s40, v10
	v_lshl_add_u64 v[12:13], v[100:101], 0, v[12:13]
	v_ashrrev_i32_e32 v15, 31, v14
	v_addc_co_u32_e32 v3, vcc, 0, v11, vcc
	v_lshlrev_b64 v[14:15], 11, v[14:15]
	v_add_co_u32_e32 v8, vcc, s41, v12
	v_lshl_add_u64 v[14:15], v[100:101], 0, v[14:15]
	s_nop 0
	v_addc_co_u32_e32 v9, vcc, 0, v13, vcc
	global_load_dwordx4 v[84:87], v[2:3], off
	global_load_dwordx4 a[0:3], v[2:3], off offset:128
	global_load_dwordx4 v[88:91], v[8:9], off
	global_load_dwordx4 a[4:7], v[8:9], off offset:128
	v_add_co_u32_e32 v2, vcc, s42, v14
	s_mov_b64 s[0:1], 0xdef
	s_nop 0
	v_addc_co_u32_e32 v3, vcc, 0, v15, vcc
	global_load_dwordx4 v[92:95], v[2:3], off
	global_load_dwordx4 a[8:11], v[2:3], off offset:128
	s_mov_b64 s[2:3], 0xdcf
	s_mov_b64 s[6:7], 0xdaf
	v_ashrrev_i32_e32 v5, 31, v4
	v_cmp_gt_i64_e32 vcc, s[0:1], v[4:5]
	v_cmp_gt_i64_e64 s[0:1], s[2:3], v[4:5]
	v_cmp_gt_i64_e64 s[6:7], s[6:7], v[4:5]
	v_lshl_add_u64 v[106:107], v[102:103], 0, v[0:1]
	v_cndmask_b32_e32 v1, 0, v5, vcc
	v_cndmask_b32_e64 v3, 0, v5, s[0:1]
	v_cndmask_b32_e64 v5, 0, v5, s[6:7]
	v_cndmask_b32_e32 v0, v117, v4, vcc
	v_cndmask_b32_e64 v2, v118, v4, s[0:1]
	v_cndmask_b32_e64 v4, v119, v4, s[6:7]
	v_mov_b32_e32 v60, 0
	v_lshlrev_b64 v[0:1], 11, v[0:1]
	v_lshlrev_b64 v[2:3], 11, v[2:3]
	v_lshlrev_b64 v[4:5], 11, v[4:5]
	s_mov_b32 s4, 0
	s_mov_b32 s5, 0
	v_mov_b32_e32 v61, v60
	v_mov_b32_e32 v62, v60
	v_mov_b32_e32 v63, v60
	v_lshl_add_u64 v[108:109], s[24:25], 0, v[6:7]
	v_lshl_add_u64 v[110:111], s[26:27], 0, v[0:1]
	v_lshl_add_u64 v[112:113], s[28:29], 0, v[2:3]
	v_lshl_add_u64 v[114:115], s[30:31], 0, v[4:5]
	v_mov_b32_e32 v56, v60
	v_mov_b32_e32 v57, v60
	v_mov_b32_e32 v58, v60
	v_mov_b32_e32 v59, v60
	v_mov_b32_e32 v52, v60
	v_mov_b32_e32 v53, v60
	v_mov_b32_e32 v54, v60
	v_mov_b32_e32 v55, v60
	v_mov_b32_e32 v48, v60
	v_mov_b32_e32 v49, v60
	v_mov_b32_e32 v50, v60
	v_mov_b32_e32 v51, v60
	v_mov_b32_e32 v44, v60
	v_mov_b32_e32 v45, v60
	v_mov_b32_e32 v46, v60
	v_mov_b32_e32 v47, v60
	v_mov_b32_e32 v40, v60
	v_mov_b32_e32 v41, v60
	v_mov_b32_e32 v42, v60
	v_mov_b32_e32 v43, v60
	v_mov_b32_e32 v36, v60
	v_mov_b32_e32 v37, v60
	v_mov_b32_e32 v38, v60
	v_mov_b32_e32 v39, v60
	v_mov_b32_e32 v32, v60
	v_mov_b32_e32 v33, v60
	v_mov_b32_e32 v34, v60
	v_mov_b32_e32 v35, v60
	v_mov_b32_e32 v28, v60
	v_mov_b32_e32 v29, v60
	v_mov_b32_e32 v30, v60
	v_mov_b32_e32 v31, v60
	v_mov_b32_e32 v24, v60
	v_mov_b32_e32 v25, v60
	v_mov_b32_e32 v26, v60
	v_mov_b32_e32 v27, v60
	v_mov_b32_e32 v20, v60
	v_mov_b32_e32 v21, v60
	v_mov_b32_e32 v22, v60
	v_mov_b32_e32 v23, v60
	v_mov_b32_e32 v16, v60
	v_mov_b32_e32 v17, v60
	v_mov_b32_e32 v18, v60
	v_mov_b32_e32 v19, v60
	v_mov_b32_e32 v12, v60
	v_mov_b32_e32 v13, v60
	v_mov_b32_e32 v14, v60
	v_mov_b32_e32 v15, v60
	v_mov_b32_e32 v8, v60
	v_mov_b32_e32 v9, v60
	v_mov_b32_e32 v10, v60
	v_mov_b32_e32 v11, v60
	v_mov_b32_e32 v4, v60
	v_mov_b32_e32 v5, v60
	v_mov_b32_e32 v6, v60
	v_mov_b32_e32 v7, v60
	v_mov_b32_e32 v0, v60
	v_mov_b32_e32 v1, v60
	v_mov_b32_e32 v2, v60
	v_mov_b32_e32 v3, v60
	s_waitcnt vmcnt(15)
	ds_write_b128 v169, v[64:67]
	s_waitcnt vmcnt(13)
	ds_write_b128 v169, v[68:71] offset:4096
	s_waitcnt vmcnt(11)
	ds_write_b128 v169, v[72:75] offset:8192
	s_waitcnt vmcnt(9)
	ds_write_b128 v169, v[76:79] offset:12288
	s_waitcnt vmcnt(7)
	ds_write_b128 v169, v[80:83] offset:16384
	s_waitcnt vmcnt(5)
	ds_write_b128 v169, v[84:87] offset:20480
	s_waitcnt vmcnt(3)
	ds_write_b128 v169, v[88:91] offset:24576
	s_waitcnt vmcnt(1)
	ds_write_b128 v169, v[92:95] offset:28672
	s_waitcnt lgkmcnt(0)
	s_barrier
	s_mov_b64 s[98:99], 0x10000
	s_branch .LBB0_112
	.p2align 6
; template <bool ABF, bool BBF, class RowF, class ColF, class Epi>
; __device__ __forceinline__ void gemm_tile(char* smem, int K, RowF rowptr, ColF colptr, int ldb, Epi epi) {
;     ...
;   for (int k0 = 0; k0 < K; k0 += BK) {
;     if (k0 + BK < K) gload(k0 + BK);
;     const u16* As = As0 + cur * (GEMM_SMEM / 2);
;     const u16* Bs = As + BM * LDT;
;     {
;       bf16x8 af[2][4], bfr[2][4];
; #pragma unroll
;       for (int ks = 0; ks < 2; ks++) {
; #pragma unroll
;         for (int mi = 0; mi < 4; mi++) af[ks][mi] = *(const bf16x8*)&As[(wm * 64 + mi * 16 + l15) * LDT + (((ks * 4 + kg) ^ swz) << 3)];
; #pragma unroll
;         for (int ni = 0; ni < 4; ni++) bfr[ks][ni] = *(const bf16x8*)&Bs[(wn * 64 + ni * 16 + l15) * LDT + (((ks * 4 + kg) ^ swz) << 3)];
;       }
;       __builtin_amdgcn_sched_barrier(0);
; #pragma unroll
;       for (int ks = 0; ks < 2; ks++)
; #pragma unroll
;         for (int mi = 0; mi < 4; mi++)
; #pragma unroll
;           for (int ni = 0; ni < 4; ni++)
;             acc[mi][ni] = __builtin_amdgcn_mfma_f32_16x16x32_bf16(bfr[ks][ni], af[ks][mi], acc[mi][ni], 0, 0, 0);
;       __builtin_amdgcn_sched_barrier(0);
;     }
.LBB0_112:
.La2_top_X:
	s_cmpk_lt_u32 s4, 0x380
	s_cbranch_scc0 .La2_nl_X
	s_lshl_b32 s6, s5, 15
	s_add_i32 s6, s6, 0
	v_lshlrev_b32_e32 v96, 1, v163
	v_lshlrev_b32_e32 v105, 1, v164
	v_add3_u32 v139, s6, v96, v105
	v_add3_u32 v141, s6, v105, v96
	ds_read_b128 v[142:145], v139
	ds_read_b128 v[146:149], v141 offset:2048
	ds_read_b128 v[150:153], v141 offset:4096
	ds_read_b128 v[154:157], v141 offset:6144
	v_lshlrev_b32_e32 v139, 1, v162
	v_add_u32_e32 v141, s6, v139
	v_add_u32_e32 v96, v141, v96
	ds_read_b128 v[172:175], v96 offset:16384
	ds_read_b128 v[176:179], v96 offset:18432
	ds_read_b128 v[180:183], v96 offset:20480
	ds_read_b128 v[184:187], v96 offset:22528
	v_lshlrev_b32_e32 v96, 1, v165
	v_add_u32_e32 v158, s6, v96
	v_add_u32_e32 v105, v158, v105
	ds_read_b128 v[188:191], v105
	ds_read_b128 v[192:195], v105 offset:2048
	ds_read_b128 v[196:199], v105 offset:4096
	ds_read_b128 v[200:203], v105 offset:6144
	v_add_u32_e32 v105, v158, v139
	v_add_u32_e32 v96, v141, v96
	ds_read_b128 v[204:207], v105 offset:16384
	ds_read_b128 v[208:211], v96 offset:18432
	ds_read_b128 v[212:215], v96 offset:20480
	ds_read_b128 v[216:219], v96 offset:22528
	s_waitcnt lgkmcnt(11)
	v_mfma_f32_16x16x32_bf16 v[60:63], v[172:175], v[142:145], v[60:63]
	s_waitcnt lgkmcnt(10)
	v_mfma_f32_16x16x32_bf16 v[56:59], v[176:179], v[142:145], v[56:59]
	s_waitcnt lgkmcnt(9)
	v_mfma_f32_16x16x32_bf16 v[52:55], v[180:183], v[142:145], v[52:55]
	s_waitcnt lgkmcnt(8)
	v_mfma_f32_16x16x32_bf16 v[48:51], v[184:187], v[142:145], v[48:51]
	v_lshl_add_u64 v[242:243], v[106:107], 0, v[124:125]
	global_load_dwordx4 v[64:67], v[242:243], off offset:256
	v_mfma_f32_16x16x32_bf16 v[44:47], v[172:175], v[146:149], v[44:47]
	v_mfma_f32_16x16x32_bf16 v[40:43], v[176:179], v[146:149], v[40:43]
	v_mfma_f32_16x16x32_bf16 v[36:39], v[180:183], v[146:149], v[36:39]
	v_mfma_f32_16x16x32_bf16 v[32:35], v[184:187], v[146:149], v[32:35]
	v_lshl_add_u64 v[242:243], v[242:243], 0, s[98:99]
	global_load_dwordx4 v[68:71], v[242:243], off offset:256
	v_mfma_f32_16x16x32_bf16 v[28:31], v[172:175], v[150:153], v[28:31]
	v_mfma_f32_16x16x32_bf16 v[24:27], v[176:179], v[150:153], v[24:27]
	v_mfma_f32_16x16x32_bf16 v[20:23], v[180:183], v[150:153], v[20:23]
	v_mfma_f32_16x16x32_bf16 v[16:19], v[184:187], v[150:153], v[16:19]
	v_lshl_add_u64 v[242:243], v[242:243], 0, s[98:99]
	global_load_dwordx4 v[72:75], v[242:243], off offset:256
	v_mfma_f32_16x16x32_bf16 v[12:15], v[172:175], v[154:157], v[12:15]
	v_mfma_f32_16x16x32_bf16 v[8:11], v[176:179], v[154:157], v[8:11]
	v_mfma_f32_16x16x32_bf16 v[4:7], v[180:183], v[154:157], v[4:7]
	v_mfma_f32_16x16x32_bf16 v[0:3], v[184:187], v[154:157], v[0:3]
	v_lshl_add_u64 v[242:243], v[242:243], 0, s[98:99]
	global_load_dwordx4 v[76:79], v[242:243], off offset:256
	s_waitcnt lgkmcnt(3)
	v_mfma_f32_16x16x32_bf16 v[60:63], v[204:207], v[188:191], v[60:63]
	s_waitcnt lgkmcnt(2)
	v_mfma_f32_16x16x32_bf16 v[56:59], v[208:211], v[188:191], v[56:59]
	s_waitcnt lgkmcnt(1)
	v_mfma_f32_16x16x32_bf16 v[52:55], v[212:215], v[188:191], v[52:55]
	s_waitcnt lgkmcnt(0)
	v_mfma_f32_16x16x32_bf16 v[48:51], v[216:219], v[188:191], v[48:51]
	v_lshl_add_u64 v[242:243], v[108:109], 0, v[124:125]
	global_load_dwordx4 v[80:83], v[242:243], off offset:128
	v_mfma_f32_16x16x32_bf16 v[44:47], v[204:207], v[192:195], v[44:47]
	v_mfma_f32_16x16x32_bf16 v[40:43], v[208:211], v[192:195], v[40:43]
	v_mfma_f32_16x16x32_bf16 v[36:39], v[212:215], v[192:195], v[36:39]
	v_mfma_f32_16x16x32_bf16 v[32:35], v[216:219], v[192:195], v[32:35]
	v_lshl_add_u64 v[242:243], v[110:111], 0, v[124:125]
	global_load_dwordx4 v[84:87], v[242:243], off offset:128
	v_mfma_f32_16x16x32_bf16 v[28:31], v[204:207], v[196:199], v[28:31]
	v_mfma_f32_16x16x32_bf16 v[24:27], v[208:211], v[196:199], v[24:27]
	v_mfma_f32_16x16x32_bf16 v[20:23], v[212:215], v[196:199], v[20:23]
	v_mfma_f32_16x16x32_bf16 v[16:19], v[216:219], v[196:199], v[16:19]
	v_lshl_add_u64 v[242:243], v[112:113], 0, v[124:125]
	global_load_dwordx4 v[88:91], v[242:243], off offset:128
	v_mfma_f32_16x16x32_bf16 v[12:15], v[204:207], v[200:203], v[12:15]
	v_mfma_f32_16x16x32_bf16 v[8:11], v[208:211], v[200:203], v[8:11]
	v_mfma_f32_16x16x32_bf16 v[4:7], v[212:215], v[200:203], v[4:7]
	v_mfma_f32_16x16x32_bf16 v[0:3], v[216:219], v[200:203], v[0:3]
	v_lshl_add_u64 v[242:243], v[114:115], 0, v[124:125]
	global_load_dwordx4 v[92:95], v[242:243], off offset:128
	s_branch .La2_cd_X

; template <bool ABF, bool BBF, class RowF, class ColF, class Epi>
; __device__ __forceinline__ void gemm_tile(char* smem, int K, RowF rowptr, ColF colptr, int ldb, Epi epi) {
;     ...
;   for (int k0 = 0; k0 < K; k0 += BK) {
;     if (k0 + BK < K) gload(k0 + BK);
;     const u16* As = As0 + cur * (GEMM_SMEM / 2);
;     const u16* Bs = As + BM * LDT;
;     {
;       bf16x8 af[2][4], bfr[2][4];
; #pragma unroll
;       for (int ks = 0; ks < 2; ks++) {
; #pragma unroll
;         for (int mi = 0; mi < 4; mi++) af[ks][mi] = *(const bf16x8*)&As[(wm * 64 + mi * 16 + l15) * LDT + (((ks * 4 + kg) ^ swz) << 3)];
; #pragma unroll
;         for (int ni = 0; ni < 4; ni++) bfr[ks][ni] = *(const bf16x8*)&Bs[(wn * 64 + ni * 16 + l15) * LDT + (((ks * 4 + kg) ^ swz) << 3)];
;       }
;       __builtin_amdgcn_sched_barrier(0);
; #pragma unroll
;       for (int ks = 0; ks < 2; ks++)
; #pragma unroll
;         for (int mi = 0; mi < 4; mi++)
; #pragma unroll
;           for (int ni = 0; ni < 4; ni++)
;             acc[mi][ni] = __builtin_amdgcn_mfma_f32_16x16x32_bf16(bfr[ks][ni], af[ks][mi], acc[mi][ni], 0, 0, 0);
;       __builtin_amdgcn_sched_barrier(0);
;     }
;     if (k0 + BK < K) sstore(cur ^ 1);
;     __syncthreads();
;     cur ^= 1;
;   }
.La2_cd_X:
	s_cmpk_lt_u32 s4, 0x3c0
	s_cbranch_scc0 .La2_nw_X
	s_lshl_b32 s2, s5, 14
	s_xor_b32 s2, s2, 0x4000
	s_lshl_b32 s2, s2, 1
	s_add_i32 s2, s2, 0
	v_lshl_add_u32 v96, v161, 1, s2
	s_cmpk_lt_u32 s4, 0x380
	s_cbranch_scc0 .La2_w7_X
	s_waitcnt vmcnt(15)
	ds_write_b128 v96, v[220:223]
	s_waitcnt vmcnt(14)
	ds_write_b128 v96, v[224:227] offset:4096
	s_waitcnt vmcnt(13)
	ds_write_b128 v96, v[228:231] offset:8192
	s_waitcnt vmcnt(12)
	ds_write_b128 v96, v[232:235] offset:12288
	s_waitcnt vmcnt(11)
	ds_write_b128 v96, v[236:239] offset:16384
	s_waitcnt vmcnt(10)
	ds_write_b128 v96, a[0:3] offset:20480
	s_waitcnt vmcnt(9)
	ds_write_b128 v96, a[4:7] offset:24576
	s_waitcnt vmcnt(8)
	ds_write_b128 v96, a[8:11] offset:28672
	s_branch .La2_nw_X
.La2_w7_X:
	s_waitcnt vmcnt(7)
	ds_write_b128 v96, v[220:223]
	s_waitcnt vmcnt(6)
	ds_write_b128 v96, v[224:227] offset:4096
	s_waitcnt vmcnt(5)
	ds_write_b128 v96, v[228:231] offset:8192
	s_waitcnt vmcnt(4)
	ds_write_b128 v96, v[232:235] offset:12288
	s_waitcnt vmcnt(3)
	ds_write_b128 v96, v[236:239] offset:16384
	s_waitcnt vmcnt(2)
	ds_write_b128 v96, a[0:3] offset:20480
	s_waitcnt vmcnt(1)
	ds_write_b128 v96, a[4:7] offset:24576
	s_waitcnt vmcnt(0)
	ds_write_b128 v96, a[8:11] offset:28672
.La2_nw_X:
	s_add_i32 s4, s4, 64
	s_xor_b32 s5, s5, 1
	v_lshl_add_u64 v[106:107], v[106:107], 0, s[22:23]
	v_lshl_add_u64 v[108:109], v[108:109], 0, s[22:23]
	v_lshl_add_u64 v[110:111], v[110:111], 0, s[22:23]
	v_lshl_add_u64 v[112:113], v[112:113], 0, s[22:23]
	v_lshl_add_u64 v[114:115], v[114:115], 0, s[22:23]
	s_waitcnt lgkmcnt(0)
	s_barrier
.La2_top_Y:
	s_cmpk_lt_u32 s4, 0x380
	s_cbranch_scc0 .La2_nl_Y
	s_lshl_b32 s6, s5, 15
	s_add_i32 s6, s6, 0
	v_lshlrev_b32_e32 v96, 1, v163
	v_lshlrev_b32_e32 v105, 1, v164
	v_add3_u32 v139, s6, v96, v105
	v_add3_u32 v141, s6, v105, v96
	ds_read_b128 v[142:145], v139
	ds_read_b128 v[146:149], v141 offset:2048
	ds_read_b128 v[150:153], v141 offset:4096
	ds_read_b128 v[154:157], v141 offset:6144
	v_lshlrev_b32_e32 v139, 1, v162
	v_add_u32_e32 v141, s6, v139
	v_add_u32_e32 v96, v141, v96
	ds_read_b128 v[172:175], v96 offset:16384
	ds_read_b128 v[176:179], v96 offset:18432
	ds_read_b128 v[180:183], v96 offset:20480
	ds_read_b128 v[184:187], v96 offset:22528
	v_lshlrev_b32_e32 v96, 1, v165
	v_add_u32_e32 v158, s6, v96
	v_add_u32_e32 v105, v158, v105
	ds_read_b128 v[188:191], v105
	ds_read_b128 v[192:195], v105 offset:2048
	ds_read_b128 v[196:199], v105 offset:4096
	ds_read_b128 v[200:203], v105 offset:6144
	v_add_u32_e32 v105, v158, v139
	v_add_u32_e32 v96, v141, v96
	ds_read_b128 v[204:207], v105 offset:16384
	ds_read_b128 v[208:211], v96 offset:18432
	ds_read_b128 v[212:215], v96 offset:20480
	ds_read_b128 v[216:219], v96 offset:22528
	s_waitcnt lgkmcnt(11)
	v_mfma_f32_16x16x32_bf16 v[60:63], v[172:175], v[142:145], v[60:63]
	s_waitcnt lgkmcnt(10)
	v_mfma_f32_16x16x32_bf16 v[56:59], v[176:179], v[142:145], v[56:59]
	s_waitcnt lgkmcnt(9)
	v_mfma_f32_16x16x32_bf16 v[52:55], v[180:183], v[142:145], v[52:55]
	s_waitcnt lgkmcnt(8)
	v_mfma_f32_16x16x32_bf16 v[48:51], v[184:187], v[142:145], v[48:51]
	v_lshl_add_u64 v[242:243], v[106:107], 0, v[124:125]
	global_load_dwordx4 v[220:223], v[242:243], off offset:256
	v_mfma_f32_16x16x32_bf16 v[44:47], v[172:175], v[146:149], v[44:47]
	v_mfma_f32_16x16x32_bf16 v[40:43], v[176:179], v[146:149], v[40:43]
	v_mfma_f32_16x16x32_bf16 v[36:39], v[180:183], v[146:149], v[36:39]
	v_mfma_f32_16x16x32_bf16 v[32:35], v[184:187], v[146:149], v[32:35]
	v_lshl_add_u64 v[242:243], v[242:243], 0, s[98:99]
	global_load_dwordx4 v[224:227], v[242:243], off offset:256
	v_mfma_f32_16x16x32_bf16 v[28:31], v[172:175], v[150:153], v[28:31]
	v_mfma_f32_16x16x32_bf16 v[24:27], v[176:179], v[150:153], v[24:27]
	v_mfma_f32_16x16x32_bf16 v[20:23], v[180:183], v[150:153], v[20:23]
	v_mfma_f32_16x16x32_bf16 v[16:19], v[184:187], v[150:153], v[16:19]
	v_lshl_add_u64 v[242:243], v[242:243], 0, s[98:99]
	global_load_dwordx4 v[228:231], v[242:243], off offset:256
	v_mfma_f32_16x16x32_bf16 v[12:15], v[172:175], v[154:157], v[12:15]
	v_mfma_f32_16x16x32_bf16 v[8:11], v[176:179], v[154:157], v[8:11]
	v_mfma_f32_16x16x32_bf16 v[4:7], v[180:183], v[154:157], v[4:7]
	v_mfma_f32_16x16x32_bf16 v[0:3], v[184:187], v[154:157], v[0:3]
	v_lshl_add_u64 v[242:243], v[242:243], 0, s[98:99]
	global_load_dwordx4 v[232:235], v[242:243], off offset:256
	s_waitcnt lgkmcnt(3)
	v_mfma_f32_16x16x32_bf16 v[60:63], v[204:207], v[188:191], v[60:63]
	s_waitcnt lgkmcnt(2)
	v_mfma_f32_16x16x32_bf16 v[56:59], v[208:211], v[188:191], v[56:59]
	s_waitcnt lgkmcnt(1)
	v_mfma_f32_16x16x32_bf16 v[52:55], v[212:215], v[188:191], v[52:55]
	s_waitcnt lgkmcnt(0)
	v_mfma_f32_16x16x32_bf16 v[48:51], v[216:219], v[188:191], v[48:51]
	v_lshl_add_u64 v[242:243], v[108:109], 0, v[124:125]
	global_load_dwordx4 v[236:239], v[242:243], off offset:128
	v_mfma_f32_16x16x32_bf16 v[44:47], v[204:207], v[192:195], v[44:47]
	v_mfma_f32_16x16x32_bf16 v[40:43], v[208:211], v[192:195], v[40:43]
	v_mfma_f32_16x16x32_bf16 v[36:39], v[212:215], v[192:195], v[36:39]
	v_mfma_f32_16x16x32_bf16 v[32:35], v[216:219], v[192:195], v[32:35]
	v_lshl_add_u64 v[242:243], v[110:111], 0, v[124:125]
	global_load_dwordx4 a[0:3], v[242:243], off offset:128
	v_mfma_f32_16x16x32_bf16 v[28:31], v[204:207], v[196:199], v[28:31]
	v_mfma_f32_16x16x32_bf16 v[24:27], v[208:211], v[196:199], v[24:27]
	v_mfma_f32_16x16x32_bf16 v[20:23], v[212:215], v[196:199], v[20:23]
	v_mfma_f32_16x16x32_bf16 v[16:19], v[216:219], v[196:199], v[16:19]
	v_lshl_add_u64 v[242:243], v[112:113], 0, v[124:125]
	global_load_dwordx4 a[4:7], v[242:243], off offset:128
	v_mfma_f32_16x16x32_bf16 v[12:15], v[204:207], v[200:203], v[12:15]
	v_mfma_f32_16x16x32_bf16 v[8:11], v[208:211], v[200:203], v[8:11]
	v_mfma_f32_16x16x32_bf16 v[4:7], v[212:215], v[200:203], v[4:7]
	v_mfma_f32_16x16x32_bf16 v[0:3], v[216:219], v[200:203], v[0:3]
	v_lshl_add_u64 v[242:243], v[114:115], 0, v[124:125]
	global_load_dwordx4 a[8:11], v[242:243], off offset:128
	s_branch .La2_cd_Y

; template <bool ABF, bool BBF, class RowF, class ColF, class Epi>
; __device__ __forceinline__ void gemm_tile(char* smem, int K, RowF rowptr, ColF colptr, int ldb, Epi epi) {
;     ...
;     if (k0 + BK < K) sstore(cur ^ 1);
;     __syncthreads();
;     cur ^= 1;
;   }
.La2_cd_Y:
	s_cmpk_lt_u32 s4, 0x3c0
	s_cbranch_scc0 .La2_nw_Y
	s_lshl_b32 s2, s5, 14
	s_xor_b32 s2, s2, 0x4000
	s_lshl_b32 s2, s2, 1
	s_add_i32 s2, s2, 0
	v_lshl_add_u32 v96, v161, 1, s2
	s_cmpk_lt_u32 s4, 0x380
	s_cbranch_scc0 .La2_w7_Y
	s_waitcnt vmcnt(15)
	ds_write_b128 v96, v[64:67]
	s_waitcnt vmcnt(14)
	ds_write_b128 v96, v[68:71] offset:4096
	s_waitcnt vmcnt(13)
	ds_write_b128 v96, v[72:75] offset:8192
	s_waitcnt vmcnt(12)
	ds_write_b128 v96, v[76:79] offset:12288
	s_waitcnt vmcnt(11)
	ds_write_b128 v96, v[80:83] offset:16384
	s_waitcnt vmcnt(10)
	ds_write_b128 v96, v[84:87] offset:20480
	s_waitcnt vmcnt(9)
	ds_write_b128 v96, v[88:91] offset:24576
	s_waitcnt vmcnt(8)
	ds_write_b128 v96, v[92:95] offset:28672
	s_branch .La2_nw_Y
.La2_w7_Y:
	s_waitcnt vmcnt(7)
	ds_write_b128 v96, v[64:67]
	s_waitcnt vmcnt(6)
	ds_write_b128 v96, v[68:71] offset:4096
	s_waitcnt vmcnt(5)
	ds_write_b128 v96, v[72:75] offset:8192
	s_waitcnt vmcnt(4)
	ds_write_b128 v96, v[76:79] offset:12288
	s_waitcnt vmcnt(3)
	ds_write_b128 v96, v[80:83] offset:16384
	s_waitcnt vmcnt(2)
	ds_write_b128 v96, v[84:87] offset:20480
	s_waitcnt vmcnt(1)
	ds_write_b128 v96, v[88:91] offset:24576
	s_waitcnt vmcnt(0)
	ds_write_b128 v96, v[92:95] offset:28672
.La2_nw_Y:
	s_add_i32 s4, s4, 64
	s_xor_b32 s5, s5, 1
	v_lshl_add_u64 v[106:107], v[106:107], 0, s[22:23]
	v_lshl_add_u64 v[108:109], v[108:109], 0, s[22:23]
	v_lshl_add_u64 v[110:111], v[110:111], 0, s[22:23]
	v_lshl_add_u64 v[112:113], v[112:113], 0, s[22:23]
	v_lshl_add_u64 v[114:115], v[114:115], 0, s[22:23]
	s_waitcnt lgkmcnt(0)
	s_barrier
	s_cmpk_lt_u32 s4, 0x400
	s_cbranch_scc1 .La2_top_X

; __global__ void __launch_bounds__(256, 2) fwd_megakernel(Params p) {
;   extern __shared__ __attribute__((aligned(16))) char smem[];
	.amdhsa_kernel _Z14fwd_megakernel6Params
		.amdhsa_group_segment_fixed_size 0
		.amdhsa_private_segment_fixed_size 0
		.amdhsa_kernarg_size 584
		.amdhsa_user_sgpr_count 2
		.amdhsa_user_sgpr_dispatch_ptr 0
		.amdhsa_user_sgpr_queue_ptr 0
		.amdhsa_user_sgpr_kernarg_segment_ptr 1
		.amdhsa_user_sgpr_dispatch_id 0
		.amdhsa_user_sgpr_kernarg_preload_length 0
		.amdhsa_user_sgpr_kernarg_preload_offset 0
		.amdhsa_user_sgpr_private_segment_size 0
		.amdhsa_uses_dynamic_stack 0
		.amdhsa_enable_private_segment 0
		.amdhsa_system_sgpr_workgroup_id_x 1
		.amdhsa_system_sgpr_workgroup_id_y 0
		.amdhsa_system_sgpr_workgroup_id_z 0
		.amdhsa_system_sgpr_workgroup_info 0
		.amdhsa_system_vgpr_workitem_id 2
		.amdhsa_next_free_vgpr 256
		.amdhsa_next_free_sgpr 102
		.amdhsa_accum_offset 244
		.amdhsa_reserve_vcc 1
		.amdhsa_float_round_mode_32 0
		.amdhsa_float_round_mode_16_64 0
		.amdhsa_float_denorm_mode_32 3
		.amdhsa_float_denorm_mode_16_64 3
		.amdhsa_dx10_clamp 1
		.amdhsa_ieee_mode 1
		.amdhsa_fp16_overflow 0
		.amdhsa_tg_split 0
		.amdhsa_exception_fp_ieee_invalid_op 0
		.amdhsa_exception_fp_denorm_src 0
		.amdhsa_exception_fp_ieee_div_zero 0
		.amdhsa_exception_fp_ieee_overflow 0
		.amdhsa_exception_fp_ieee_underflow 0
		.amdhsa_exception_fp_ieee_inexact 0
		.amdhsa_exception_int_div_zero 0
	.end_amdhsa_kernel

; __global__ void __launch_bounds__(256, 2) fwd_megakernel(Params p) {
;   extern __shared__ __attribute__((aligned(16))) char smem[];
amdhsa.kernels:
  - .agpr_count:     12
    .args:
      - .offset:         0
        .size:           328
        .value_kind:     by_value
      - .offset:         328
        .size:           4
        .value_kind:     hidden_block_count_x
      - .offset:         332
        .size:           4
        .value_kind:     hidden_block_count_y
      - .offset:         336
        .size:           4
        .value_kind:     hidden_block_count_z
      - .offset:         340
        .size:           2
        .value_kind:     hidden_group_size_x
      - .offset:         342
        .size:           2
        .value_kind:     hidden_group_size_y
      - .offset:         344
        .size:           2
        .value_kind:     hidden_group_size_z
      - .offset:         346
        .size:           2
        .value_kind:     hidden_remainder_x
      - .offset:         348
        .size:           2
        .value_kind:     hidden_remainder_y
      - .offset:         350
        .size:           2
        .value_kind:     hidden_remainder_z
      - .offset:         368
        .size:           8
        .value_kind:     hidden_global_offset_x
      - .offset:         376
        .size:           8
        .value_kind:     hidden_global_offset_y
      - .offset:         384
        .size:           8
        .value_kind:     hidden_global_offset_z
      - .offset:         392
        .size:           2
        .value_kind:     hidden_grid_dims
      - .offset:         416
        .size:           8
        .value_kind:     hidden_multigrid_sync_arg
      - .offset:         448
        .size:           4
        .value_kind:     hidden_dynamic_lds_size
    .group_segment_fixed_size: 0
    .kernarg_segment_align: 8
    .kernarg_segment_size: 584
    .language:       OpenCL C
    .language_version:
      - 2
      - 0
    .max_flat_workgroup_size: 256
    .name:           _Z14fwd_megakernel6Params
    .private_segment_fixed_size: 0
    .sgpr_count:     108
    .sgpr_spill_count: 57
    .symbol:         _Z14fwd_megakernel6Params.kd
    .uniform_work_group_size: 1
    .uses_dynamic_stack: false
    .vgpr_count:     244
    .vgpr_spill_count: 0
    .wavefront_size: 64
